# attention work queue: next unit ticket fetched at the start of the current unit (on the P5/P7 bundle)
# speedup vs baseline: 1.0110x; 1.0000x over previous
.LBB0_809:
	s_or_b64 exec, exec, s[0:1]
	s_mov_b64 s[0:1], s[92:93]
	s_waitcnt lgkmcnt(0)
	s_barrier
	s_load_dwordx2 s[12:13], s[0:1], 0xd8
	v_mov_b32_e32 v187, v230
	v_mov_b32_e32 v0, 0x3f80
	v_and_b32_e32 v189, 63, v187
	s_waitcnt lgkmcnt(0)
	s_add_u32 s0, s12, 0x186a0000
	s_addc_u32 s1, s13, 0
	v_writelane_b32 v252, s0, 12
	v_cmp_gt_u32_e64 s[6:7], 32, v189
	v_mov_b32_e32 v1, 0x5040100
	v_writelane_b32 v252, s1, 13
	s_add_u32 s0, s12, 0x32a0000
	s_addc_u32 s1, s13, 0
	v_writelane_b32 v252, s0, 14
	v_cndmask_b32_e64 v0, 0, v0, s[6:7]
	v_perm_b32 v129, 0, v0, v1
	v_writelane_b32 v252, s1, 15
	s_add_u32 s0, s12, 0x30a0000
	v_writelane_b32 v252, s0, 16
	s_addc_u32 s0, s13, 0
	v_writelane_b32 v252, s0, 17
	s_add_u32 s0, s12, 0x3ca0000
	v_writelane_b32 v252, s0, 18
	s_addc_u32 s0, s13, 0
	v_writelane_b32 v252, s0, 19
	s_add_u32 s0, s12, 0x3da0000
	v_writelane_b32 v252, s0, 20
	s_addc_u32 s0, s13, 0
	v_writelane_b32 v252, s0, 21
	s_add_u32 s0, s12, 0x106a0000
	s_addc_u32 s1, s13, 0
	v_writelane_b32 v252, s0, 22
	s_mov_b64 s[2:3], 0x8000
	v_cmp_eq_u32_e64 s[4:5], 0, v187
	v_writelane_b32 v252, s1, 23
	s_add_u32 s0, s12, 0x146a0000
	s_addc_u32 s1, s13, 0
	v_writelane_b32 v252, s0, 24
	v_bfe_u32 v3, v187, 5, 1
	v_and_b32_e32 v5, 7, v187
	v_writelane_b32 v252, s1, 25
	s_add_u32 s0, s12, 0x8000
	s_addc_u32 s1, s13, 0
	v_writelane_b32 v252, s0, 26
	v_lshlrev_b32_e32 v4, 3, v5
	v_lshlrev_b32_e32 v5, 4, v5
	v_writelane_b32 v252, s1, 27
	s_mov_b32 s0, 0x5040100
	v_perm_b32 v128, v0, v0, s0
	v_ashrrev_i32_e32 v0, 3, v187
	v_ashrrev_i32_e32 v1, 31, v0
	s_pack_ll_b32_b16 s0, 0, 0
	v_lshlrev_b64 v[198:199], 8, v[0:1]
	v_writelane_b32 v252, s4, 28
	v_mov_b32_e32 v130, s0
	v_mov_b32_e32 v131, s0
	s_movk_i32 s0, 0x1300
	v_lshl_add_u64 v[202:203], v[198:199], 0, s[2:3]
	s_mov_b64 s[2:3], 0xc000
	v_writelane_b32 v252, s5, 29
	v_mad_i64_i32 v[190:191], s[4:5], v0, s0, 0
	s_movk_i32 s0, 0x90
	v_lshl_add_u64 v[204:205], v[198:199], 0, s[2:3]
	v_cmp_ne_u32_e64 s[2:3], 0, v189
	v_mul_lo_u32 v8, v0, s0
	v_lshrrev_b32_e32 v6, 2, v187
	v_and_b32_e32 v7, 16, v187
	v_lshlrev_b32_e32 v196, 2, v3
	v_lshlrev_b32_e32 v234, 2, v189
	v_writelane_b32 v252, s2, 30
	v_lshlrev_b32_e32 v188, 3, v3
	v_add_u32_e32 v197, v8, v5
	v_lshlrev_b32_e32 v233, 4, v3
	v_and_or_b32 v3, v6, 3, v196
	v_and_or_b32 v6, v234, 12, v7
	v_writelane_b32 v252, s3, 31
	v_cmp_eq_u32_e64 s[2:3], 0, v189
	v_and_b32_e32 v193, 31, v187
	v_add_u32_e32 v192, 0, v197
	v_mul_u32_u24_e32 v3, 0xc0, v3
	v_lshlrev_b32_e32 v6, 1, v6
	v_writelane_b32 v252, s2, 32
	s_movk_i32 s70, 0x2600
	v_mad_u64_u32 v[194:195], s[4:5], v0, 48, v[192:193]
	v_add3_u32 v235, 0, v3, v6
	v_lshlrev_b64 v[6:7], 7, v[0:1]
	v_writelane_b32 v252, s3, 33
	v_mad_i64_i32 v[0:1], s[2:3], v0, s70, 0
	v_bfe_u32 v236, v187, 3, 3
	v_or_b32_e32 v0, v0, v5
	v_and_b32_e32 v237, 4, v236
	v_lshl_add_u64 v[0:1], s[12:13], 0, v[0:1]
	s_mov_b64 s[2:3], 0x186a0e00
	v_lshl_add_u64 v[206:207], v[0:1], 0, s[2:3]
	v_lshl_or_b32 v0, v193, 8, v237
	v_mad_u32_u24 v232, v193, s0, 0
	v_or_b32_e32 v6, v6, v4
	s_mov_b64 s[4:5], 0x4000
	v_add_u32_e32 v3, 0, v8
	v_add_u32_e32 v0, 0, v0
	s_mov_b32 s1, 0
	v_mov_b32_e32 v2, 0
	v_or_b32_e32 v190, v190, v4
	v_cmp_gt_i32_e64 s[8:9], 64, v187
	v_cmp_lt_i32_e64 s[10:11], 63, v187
	v_mul_lo_u32 v195, v187, s0
	v_add_u32_e32 v238, 0, v234
	v_add_u32_e32 v239, v232, v233
	v_lshl_add_u32 v240, v187, 3, 0
	v_lshl_add_u64 v[200:201], v[198:199], 0, s[4:5]
	v_lshl_add_u32 v241, v189, 3, 0
	v_add_u32_e32 v242, 0xb000, v0
	s_add_i32 s97, 0, 0x20080
	s_movk_i32 s3, 0xffe0
	s_mov_b32 s4, 0xffff
	s_mov_b32 s5, 0xff800000
	s_mov_b32 s14, 0x40c00000
	v_lshlrev_b32_e32 v208, 1, v4
	v_mov_b32_e32 v243, 0x98000
	v_mov_b32_e32 v244, 0xff800000
	v_mbcnt_hi_u32_b32 v231, -1, v220
	v_lshlrev_b64 v[210:211], 1, v[6:7]
	v_add_u32_e32 v245, v3, v5
	s_mov_b32 s15, 0
	v_writelane_b32 v252, s94, 34
	s_nop 1
	v_writelane_b32 v252, s95, 35
	s_mov_b32 s98, 0
	s_branch .LBB0_811

.LBB0_811:
	s_getreg_b32 s0, hwreg(HW_REG_XCC_ID, 0, 4)
	s_add_i32 s0, s0, s15
	s_and_b32 s58, s0, 7
	s_mov_b64 s[12:13], exec
	v_readlane_b32 s16, v252, 28
	v_readlane_b32 s17, v252, 29
	s_and_b64 s[16:17], s[12:13], s[16:17]
	s_mov_b64 exec, s[16:17]
	s_cbranch_execz .LBB0_815
	s_mov_b64 s[18:19], exec
	v_mbcnt_lo_u32_b32 v0, s18, 0
	v_mbcnt_hi_u32_b32 v0, s19, v0
	v_cmp_eq_u32_e32 vcc, 0, v0
	s_and_saveexec_b64 s[16:17], vcc
	s_cbranch_execz .LBB0_814
	s_cmp_lg_u32 s98, 0
	s_cbranch_scc1 .Lq_have
	s_lshl_b32 s0, s58, 8
	s_bcnt1_i32_b64 s2, s[18:19]
	v_readlane_b32 s18, v252, 26
	v_mov_b32_e32 v1, s0
	v_mov_b32_e32 v3, s2
	v_readlane_b32 s19, v252, 27
	s_nop 4
	global_atomic_add v1, v1, v3, s[18:19] sc0
	s_branch .LBB0_814
.Lq_have:
	s_waitcnt vmcnt(0)
	v_mov_b32_e32 v1, v253

.LBB0_815:
	s_or_b64 exec, exec, s[12:13]
	s_mov_b32 s98, 0
	v_mov_b32_e32 v0, s97
	s_waitcnt lgkmcnt(0)
	s_barrier
	ds_read_b32 v0, v0
	s_movk_i32 s0, 0x200
	s_mov_b64 s[12:13], -1
	s_waitcnt lgkmcnt(0)
	s_barrier
	v_cmp_gt_u32_e32 vcc, s0, v0
	v_readfirstlane_b32 s62, v0
	s_cbranch_vccz .LBB0_864
	s_mov_b32 s98, 1
	s_mov_b64 s[100:101], exec
	v_readlane_b32 vcc_lo, v252, 28
	v_readlane_b32 vcc_hi, v252, 29
	s_nop 1
	s_and_b64 vcc, exec, vcc
	s_mov_b64 exec, vcc
	s_cbranch_execz .Lq_pf_done
	s_lshl_b32 s99, s58, 8
	v_readlane_b32 vcc_lo, v252, 26
	v_readlane_b32 vcc_hi, v252, 27
	v_mov_b32_e32 v254, s99
	v_mov_b32_e32 v255, 1
	s_nop 4
	global_atomic_add v253, v254, v255, vcc sc0
.Lq_pf_done:
	s_mov_b64 exec, s[100:101]
	s_lshr_b32 s59, s62, 5
	s_and_b32 s60, s62, 31
	s_cmp_gt_u32 s60, 15
	v_lshlrev_b32_e32 v168, 1, v188
	s_cbranch_scc0 .LBB0_867
	s_add_i32 s0, s60, -16
	s_lshl_b32 s2, s59, 2
	s_and_b32 s2, s2, 12
	s_lshr_b32 s0, s0, 2
	s_add_i32 s20, s2, s0
	s_and_b32 s0, s59, 12
	s_xor_b32 s2, s0, 15
	s_and_b32 s22, s62, 3
	v_readfirstlane_b32 s0, v187
	s_sub_i32 s16, s2, s22
	s_ashr_i32 s0, s0, 1
	s_lshl_b32 s12, s16, 8
	s_and_b32 s23, s0, 0xffffffe0
	s_add_i32 s23, s23, s12
	v_or_b32_e32 v172, s23, v193
	v_readlane_b32 s18, v252, 12
	s_lshl_b32 s0, s20, 12
	s_waitcnt vmcnt(10)
	v_ashrrev_i32_e32 v173, 31, v172
	v_readlane_b32 s19, v252, 13
	v_lshl_add_u64 v[170:171], v[172:173], 0, s[0:1]
	s_mul_i32 s24, s20, 0x2600000
	v_mov_b64_e32 v[0:1], s[18:19]
	v_mad_u64_u32 v[0:1], s[12:13], v170, s70, v[0:1]
	v_mad_i32_i24 v1, v171, s70, v1
	s_lshl_b32 s12, s58, 7
	s_mov_b32 s13, s1
	v_lshl_add_u64 v[0:1], v[0:1], 0, s[12:13]
	s_lshl_b32 s13, s16, 2
	s_mul_hi_u32 s25, s0, 0x2600
	s_add_u32 s0, s18, s24
	s_addc_u32 s17, s19, s25
	s_add_u32 s16, s0, s12
	s_addc_u32 s17, s17, 0
	s_add_u32 s18, s16, 0x1200
	s_addc_u32 s19, s17, 0
	s_lshl_b32 s0, s20, 15
	s_lshl_b32 s20, s58, 12
	s_or_b32 s0, s0, s20
	s_lshl_b64 s[20:21], s[0:1], 2
	v_readlane_b32 s0, v252, 16
	s_add_u32 s52, s0, s20
	v_readlane_b32 s0, v252, 17
	s_addc_u32 s53, s0, s21
	s_or_b32 s66, s13, 3
	s_mul_i32 s0, s66, 0x4c000
	s_lshl_b32 s26, s0, 1
	s_waitcnt vmcnt(8)
	v_mov_b32_e32 v169, v2
	s_add_u32 s20, s16, s26
	v_lshl_add_u64 v[0:1], v[0:1], 0, v[168:169]
	s_addc_u32 s21, s17, 0
	v_lshlrev_b64 v[4:5], 1, v[190:191]
	global_load_dwordx4 v[112:115], v[0:1], off offset:2560
	global_load_dwordx4 v[116:119], v[0:1], off offset:2592
	global_load_dwordx4 v[120:123], v[0:1], off offset:2624
	global_load_dwordx4 v[124:127], v[0:1], off offset:2656
	v_lshl_add_u64 v[0:1], s[20:21], 0, v[4:5]
	s_add_u32 s20, s18, s26
	s_addc_u32 s21, s19, 0
	v_lshl_add_u64 v[6:7], s[20:21], 0, v[4:5]
	global_load_dwordx4 v[132:135], v[0:1], off offset:3584
	global_load_dwordx4 v[136:139], v[6:7], off
	v_mov_b32_e32 v169, 0
	v_mov_b32_e32 v173, 0
	s_and_saveexec_b64 s[20:21], s[8:9]
	s_cbranch_execz .LBB0_819
	v_lshl_add_u32 v0, s66, 6, v187
	v_ashrrev_i32_e32 v1, 31, v0
	v_lshl_add_u64 v[0:1], v[0:1], 2, s[52:53]
	global_load_dword v173, v[0:1], off

	.amdhsa_kernel _Z8mega_fwd6Params
		.amdhsa_group_segment_fixed_size 0
		.amdhsa_private_segment_fixed_size 0
		.amdhsa_kernarg_size 480
		.amdhsa_user_sgpr_count 2
		.amdhsa_user_sgpr_dispatch_ptr 0
		.amdhsa_user_sgpr_queue_ptr 0
		.amdhsa_user_sgpr_kernarg_segment_ptr 1
		.amdhsa_user_sgpr_dispatch_id 0
		.amdhsa_user_sgpr_kernarg_preload_length 0
		.amdhsa_user_sgpr_kernarg_preload_offset 0
		.amdhsa_user_sgpr_private_segment_size 0
		.amdhsa_uses_dynamic_stack 0
		.amdhsa_enable_private_segment 0
		.amdhsa_system_sgpr_workgroup_id_x 1
		.amdhsa_system_sgpr_workgroup_id_y 0
		.amdhsa_system_sgpr_workgroup_id_z 0
		.amdhsa_system_sgpr_workgroup_info 0
		.amdhsa_system_vgpr_workitem_id 2
		.amdhsa_next_free_vgpr 256
		.amdhsa_next_free_sgpr 102
		.amdhsa_accum_offset 256
		.amdhsa_reserve_vcc 1
		.amdhsa_float_round_mode_32 0
		.amdhsa_float_round_mode_16_64 0
		.amdhsa_float_denorm_mode_32 3
		.amdhsa_float_denorm_mode_16_64 3
		.amdhsa_dx10_clamp 1
		.amdhsa_ieee_mode 1
		.amdhsa_fp16_overflow 0
		.amdhsa_tg_split 0
		.amdhsa_exception_fp_ieee_invalid_op 0
		.amdhsa_exception_fp_denorm_src 0
		.amdhsa_exception_fp_ieee_div_zero 0
		.amdhsa_exception_fp_ieee_overflow 0
		.amdhsa_exception_fp_ieee_underflow 0
		.amdhsa_exception_fp_ieee_inexact 0
		.amdhsa_exception_int_div_zero 0
	.end_amdhsa_kernel

amdhsa.kernels:
  - .agpr_count:     0
    .args:
      - .offset:         0
        .size:           224
        .value_kind:     by_value
      - .offset:         224
        .size:           4
        .value_kind:     hidden_block_count_x
      - .offset:         228
        .size:           4
        .value_kind:     hidden_block_count_y
      - .offset:         232
        .size:           4
        .value_kind:     hidden_block_count_z
      - .offset:         236
        .size:           2
        .value_kind:     hidden_group_size_x
      - .offset:         238
        .size:           2
        .value_kind:     hidden_group_size_y
      - .offset:         240
        .size:           2
        .value_kind:     hidden_group_size_z
      - .offset:         242
        .size:           2
        .value_kind:     hidden_remainder_x
      - .offset:         244
        .size:           2
        .value_kind:     hidden_remainder_y
      - .offset:         246
        .size:           2
        .value_kind:     hidden_remainder_z
      - .offset:         264
        .size:           8
        .value_kind:     hidden_global_offset_x
      - .offset:         272
        .size:           8
        .value_kind:     hidden_global_offset_y
      - .offset:         280
        .size:           8
        .value_kind:     hidden_global_offset_z
      - .offset:         288
        .size:           2
        .value_kind:     hidden_grid_dims
      - .offset:         312
        .size:           8
        .value_kind:     hidden_multigrid_sync_arg
      - .offset:         344
        .size:           4
        .value_kind:     hidden_dynamic_lds_size
    .group_segment_fixed_size: 0
    .kernarg_segment_align: 8
    .kernarg_segment_size: 480
    .language:       OpenCL C
    .language_version:
      - 2
      - 0
    .max_flat_workgroup_size: 512
    .name:           _Z8mega_fwd6Params
    .private_segment_fixed_size: 0
    .sgpr_count:     108
    .sgpr_spill_count: 36
    .symbol:         _Z8mega_fwd6Params.kd
    .uniform_work_group_size: 1
    .uses_dynamic_stack: false
    .vgpr_count:     256
    .vgpr_spill_count: 0
    .wavefront_size: 64
